# P0 weight-copy stores staged through LDS: 8 full 128B lines per store instruction instead of 64 row-per-lane 16B pieces
# baseline (speedup 1.0000x reference)
; __device__ __forceinline__ unsigned pk2(float lo, float hi) { typedef float f2_t __attribute__((ext_vector_type(2))); typedef __bf16 b2_t __attribute__((ext_vector_type(2))); const f2_t v = {lo, hi}; return __builtin_bit_cast(unsigned, __builtin_convertvector(v, b2_t)); }
; __device__ __forceinline__ void transpose_item(const float* W, int K, int N, bf16* WT, int mode, int row_off, const float* gain, int item, int lane) {
;     ...
;     bf16* dst = WT + (size_t)(rbase + lane) * K + k0;
; #pragma unroll
;     for (int c = 0; c < 8; ++c) { v4u o; o.x = pk2(v[8 * c], v[8 * c + 1]); o.y = pk2(v[8 * c + 2], v[8 * c + 3]); o.z = pk2(v[8 * c + 4], v[8 * c + 5]); o.w = pk2(v[8 * c + 6], v[8 * c + 7]);
;         *(v4u*)(dst + 8 * c) = o; }
.LBB0_22:
	s_waitcnt vmcnt(0)
	v_cvt_pk_bf16_f32 v60, v2, v3
	v_cvt_pk_bf16_f32 v2, v4, v5
	v_cvt_pk_bf16_f32 v3, v12, v13
	v_cvt_pk_bf16_f32 v4, v16, v17
	v_cvt_pk_bf16_f32 v5, v18, v19
	ds_write_b128 v200, v[2:5] offset:32
	s_nop 1
	s_add_i32 s62, s62, s38
	s_add_i32 s2, s2, s3
	v_cvt_pk_bf16_f32 v2, v14, v15
	v_cvt_pk_bf16_f32 v3, v20, v21
	v_cvt_pk_bf16_f32 v4, v24, v25
	v_cvt_pk_bf16_f32 v5, v26, v27
	ds_write_b128 v200, v[2:5] offset:48
	s_nop 1
	s_add_i32 s8, s8, s9
	s_add_i32 s10, s10, s11
	v_cvt_pk_bf16_f32 v2, v22, v23
	v_cvt_pk_bf16_f32 v3, v28, v29
	v_cvt_pk_bf16_f32 v4, v32, v33
	v_cvt_pk_bf16_f32 v5, v34, v35
	ds_write_b128 v200, v[2:5] offset:64
	s_nop 1
	v_cvt_pk_bf16_f32 v61, v6, v7
	v_cvt_pk_bf16_f32 v62, v8, v9
	v_cvt_pk_bf16_f32 v2, v30, v31
	v_cvt_pk_bf16_f32 v3, v36, v37
	v_cvt_pk_bf16_f32 v4, v40, v41
	v_cvt_pk_bf16_f32 v5, v42, v43
	ds_write_b128 v200, v[2:5] offset:80
	s_nop 1
	v_cvt_pk_bf16_f32 v63, v10, v11
	s_cmpk_gt_i32 s62, 0x2fff
	v_cvt_pk_bf16_f32 v2, v38, v39
	v_cvt_pk_bf16_f32 v3, v44, v45
	v_cvt_pk_bf16_f32 v4, v48, v49
	v_cvt_pk_bf16_f32 v5, v50, v51
	ds_write_b128 v200, v[2:5] offset:96
	s_nop 1
	ds_write_b128 v200, v[60:63] offset:16
	s_nop 1
	s_nop 0
	v_cvt_pk_bf16_f32 v2, v46, v47
	v_cvt_pk_bf16_f32 v3, v52, v53
	v_cvt_pk_bf16_f32 v4, v54, v55
	v_cvt_pk_bf16_f32 v5, v56, v57
	ds_write_b128 v200, v[2:5] offset:112
	s_nop 1
	v_lshrrev_b32_e32 v202, 3, v188
	v_and_b32_e32 v203, 7, v188
	v_lshrrev_b32_e32 v201, 6, v189
	v_lshlrev_b32_e32 v203, 4, v203
	v_mul_u32_u24_e32 v201, 0x2400, v201
	v_mul_u32_u24_e32 v204, 0x90, v202
	v_add3_u32 v201, v201, v204, v203
	ds_read_b128 v[208:211], v201
	ds_read_b128 v[212:215], v201 offset:1152
	ds_read_b128 v[216:219], v201 offset:2304
	ds_read_b128 v[220:223], v201 offset:3456
	ds_read_b128 v[224:227], v201 offset:4608
	ds_read_b128 v[228:231], v201 offset:5760
	ds_read_b128 v[232:235], v201 offset:6912
	ds_read_b128 v[236:239], v201 offset:8064
	v_readlane_b32 s0, v58, 0
	v_readlane_b32 s1, v59, 0
	v_readlane_b32 vcc_lo, v58, 1
	s_nop 1
	v_mov_b32_e32 v205, vcc_lo
	v_subrev_u32_e32 v205, s0, v205
	v_mul_lo_u32 v206, v202, v205
	v_add_u32_e32 v206, v206, v203
	v_lshlrev_b32_e32 v205, 3, v205
	s_waitcnt lgkmcnt(0)
	global_store_dwordx4 v206, v[208:211], s[0:1]
	v_add_u32_e32 v207, v206, v205
	global_store_dwordx4 v207, v[212:215], s[0:1]
	v_add_u32_e32 v206, v207, v205
	global_store_dwordx4 v206, v[216:219], s[0:1]
	v_add_u32_e32 v207, v206, v205
	global_store_dwordx4 v207, v[220:223], s[0:1]
	v_add_u32_e32 v206, v207, v205
	global_store_dwordx4 v206, v[224:227], s[0:1]
	v_add_u32_e32 v207, v206, v205
	global_store_dwordx4 v207, v[228:231], s[0:1]
	v_add_u32_e32 v206, v207, v205
	global_store_dwordx4 v206, v[232:235], s[0:1]
	v_add_u32_e32 v207, v206, v205
	global_store_dwordx4 v207, v[236:239], s[0:1]
	s_cbranch_scc1 .LBB0_43

; __device__ __forceinline__ unsigned pk2(float lo, float hi) { typedef float f2_t __attribute__((ext_vector_type(2))); typedef __bf16 b2_t __attribute__((ext_vector_type(2))); const f2_t v = {lo, hi}; return __builtin_bit_cast(unsigned, __builtin_convertvector(v, b2_t)); }
; __device__ __forceinline__ void transpose_item(const float* W, int K, int N, bf16* WT, int mode, int row_off, const float* gain, int item, int lane) {
;     ...
;     bf16* dst = WT + (size_t)(rbase + lane) * K + k0;
; #pragma unroll
;     for (int c = 0; c < 8; ++c) { v4u o; o.x = pk2(v[8 * c], v[8 * c + 1]); o.y = pk2(v[8 * c + 2], v[8 * c + 3]); o.z = pk2(v[8 * c + 4], v[8 * c + 5]); o.w = pk2(v[8 * c + 6], v[8 * c + 7]);
;         *(v4u*)(dst + 8 * c) = o; }
.LBB0_29:
	v_readlane_b32 s72, v255, 6
	v_add_lshl_u32 v58, s64, v96, 12
	v_mov_b32_e32 v59, v1
	v_readlane_b32 s73, v255, 7
	s_lshl_b32 s30, s30, 1
	s_waitcnt vmcnt(7)
	v_cvt_pk_bf16_f32 v62, v62, v63
	v_lshl_add_u64 v[58:59], s[72:73], 0, v[58:59]
	v_lshl_add_u64 v[58:59], v[58:59], 0, s[30:31]
	v_cvt_pk_bf16_f32 v63, v60, v61
	v_cvt_pk_bf16_f32 v64, v64, v65
	v_cvt_pk_bf16_f32 v65, v66, v67
	v_lshrrev_b32_e32 v200, 6, v189
	v_mul_u32_u24_e32 v201, 0x90, v188
	v_mul_u32_u24_e32 v200, 0x2400, v200
	v_add_u32_e32 v200, v200, v201
	ds_write_b128 v200, v[62:65]
	s_nop 1
	s_mov_b64 s[72:73], 0

; __device__ __forceinline__ unsigned pk2(float lo, float hi) { typedef float f2_t __attribute__((ext_vector_type(2))); typedef __bf16 b2_t __attribute__((ext_vector_type(2))); const f2_t v = {lo, hi}; return __builtin_bit_cast(unsigned, __builtin_convertvector(v, b2_t)); }
; __device__ __forceinline__ void transpose_item(const float* W, int K, int N, bf16* WT, int mode, int row_off, const float* gain, int item, int lane) {
;     ...
;     bf16* dst = WT + (size_t)(rbase + lane) * K + k0;
; #pragma unroll
;     for (int c = 0; c < 8; ++c) { v4u o; o.x = pk2(v[8 * c], v[8 * c + 1]); o.y = pk2(v[8 * c + 2], v[8 * c + 3]); o.z = pk2(v[8 * c + 4], v[8 * c + 5]); o.w = pk2(v[8 * c + 6], v[8 * c + 7]);
;         *(v4u*)(dst + 8 * c) = o; }
.LBB0_33:
	s_lshl_b32 s0, s64, 6
	s_and_b32 s0, 0xffff, s0
	v_or_b32_e32 v58, s0, v188
	v_readlane_b32 s0, v255, 6
	v_lshlrev_b32_e32 v58, 12, v58
	v_mov_b32_e32 v59, v1
	v_readlane_b32 s1, v255, 7
	s_lshl_b32 s30, s30, 1
	s_waitcnt vmcnt(7)
	v_cvt_pk_bf16_f32 v62, v62, v63
	v_lshl_add_u64 v[58:59], s[0:1], 0, v[58:59]
	v_lshl_add_u64 v[58:59], v[58:59], 0, s[30:31]
	v_cvt_pk_bf16_f32 v63, v60, v61
	v_cvt_pk_bf16_f32 v64, v64, v65
	v_cvt_pk_bf16_f32 v65, v66, v67
	v_lshrrev_b32_e32 v200, 6, v189
	v_mul_u32_u24_e32 v201, 0x90, v188
	v_mul_u32_u24_e32 v200, 0x2400, v200
	v_add_u32_e32 v200, v200, v201
	ds_write_b128 v200, v[62:65]
	s_nop 1
	s_mov_b64 s[0:1], 0

; __device__ __forceinline__ void transpose_item(const float* W, int K, int N, bf16* WT, int mode, int row_off, const float* gain, int item, int lane) {
;     ...
;     const float* src = W + (size_t)k0 * N + n0 + lane;
;     float v[64];
; #pragma unroll
;     for (int i = 0; i < 64; ++i) v[i] = src[(size_t)i * N];
.LBB0_35:
	s_and_b32 s30, s10, 0x1ffc0
	v_readlane_b32 s76, v254, 7
	s_and_b32 s64, s2, 0x7c0
	s_lshl_b32 s0, s30, 13
	v_readlane_b32 s84, v254, 15
	v_readlane_b32 s85, v254, 16
	s_add_u32 s0, s84, s0
	s_addc_u32 s1, s85, 0
	s_lshl_b32 s72, s64, 2
	s_add_u32 s0, s0, s72
	s_addc_u32 s1, s1, 0
	v_lshl_add_u64 v[2:3], s[0:1], 0, v[0:1]
	s_movk_i32 s72, 0x2000
	v_add_co_u32_e32 v4, vcc, s72, v2
	s_movk_i32 s72, 0x4000
	s_nop 0
	v_addc_co_u32_e32 v5, vcc, 0, v3, vcc
	v_add_co_u32_e32 v6, vcc, s72, v2
	s_movk_i32 s72, 0x6000
	s_nop 0
	v_addc_co_u32_e32 v7, vcc, 0, v3, vcc
	v_add_co_u32_e32 v8, vcc, s72, v2
	s_mov_b32 s72, 0x8000
	s_nop 0
	v_addc_co_u32_e32 v9, vcc, 0, v3, vcc
	v_add_co_u32_e32 v10, vcc, s72, v2
	s_mov_b32 s72, 0xa000
	s_nop 0
	v_addc_co_u32_e32 v11, vcc, 0, v3, vcc
	v_add_co_u32_e32 v12, vcc, s72, v2
	s_mov_b32 s72, 0xc000
	s_nop 0
	v_addc_co_u32_e32 v13, vcc, 0, v3, vcc
	v_add_co_u32_e32 v14, vcc, s72, v2
	s_mov_b32 s72, 0xe000
	s_nop 0
	v_addc_co_u32_e32 v15, vcc, 0, v3, vcc
	v_add_co_u32_e32 v16, vcc, s72, v2
	s_mov_b32 s72, 0x12000
	s_nop 0
	v_addc_co_u32_e32 v17, vcc, 0, v3, vcc
	v_add_co_u32_e32 v18, vcc, s15, v2
	s_lshl_b32 s30, s30, 1
	s_nop 0
	v_addc_co_u32_e32 v19, vcc, 0, v3, vcc
	v_add_co_u32_e32 v20, vcc, s72, v2
	s_mov_b32 s72, 0x14000
	s_nop 0
	v_addc_co_u32_e32 v21, vcc, 0, v3, vcc
	v_add_co_u32_e32 v22, vcc, s72, v2
	s_mov_b32 s72, 0x18000
	s_nop 0
	v_addc_co_u32_e32 v23, vcc, 0, v3, vcc
	v_add_co_u32_e32 v24, vcc, s17, v2
	v_readlane_b32 s77, v254, 8
	s_nop 0
	v_addc_co_u32_e32 v25, vcc, 0, v3, vcc
	v_add_co_u32_e32 v26, vcc, s72, v2
	s_mov_b32 s72, 0x1a000
	s_nop 0
	v_addc_co_u32_e32 v27, vcc, 0, v3, vcc
	v_add_co_u32_e32 v28, vcc, s72, v2
	s_mov_b32 s72, 0x1c000
	s_nop 0
	v_addc_co_u32_e32 v29, vcc, 0, v3, vcc
	v_add_co_u32_e32 v30, vcc, s72, v2
	s_mov_b32 s72, 0x1e000
	s_nop 0
	v_addc_co_u32_e32 v31, vcc, 0, v3, vcc
	v_add_co_u32_e32 v32, vcc, s72, v2
	s_mov_b32 s72, 0x20000
	s_nop 0
	v_addc_co_u32_e32 v33, vcc, 0, v3, vcc
	v_add_co_u32_e32 v34, vcc, s72, v2
	s_mov_b32 s72, 0x22000
	s_nop 0
	v_addc_co_u32_e32 v35, vcc, 0, v3, vcc
	v_add_co_u32_e32 v36, vcc, s72, v2
	s_mov_b32 s72, 0x24000
	s_nop 0
	v_addc_co_u32_e32 v37, vcc, 0, v3, vcc
	v_add_co_u32_e32 v38, vcc, s72, v2
	s_mov_b32 s72, 0x28000
	s_nop 0
	v_addc_co_u32_e32 v39, vcc, 0, v3, vcc
	v_add_co_u32_e32 v40, vcc, s63, v2
	v_readlane_b32 s78, v254, 9
	s_nop 0
	v_addc_co_u32_e32 v41, vcc, 0, v3, vcc
	v_add_co_u32_e32 v42, vcc, s72, v2
	s_mov_b32 s72, 0x2a000
	s_nop 0
	v_addc_co_u32_e32 v43, vcc, 0, v3, vcc
	v_add_co_u32_e32 v44, vcc, s72, v2
	s_mov_b32 s72, 0x2e000
	s_nop 0
	v_addc_co_u32_e32 v45, vcc, 0, v3, vcc
	v_add_co_u32_e32 v46, vcc, s22, v2
	v_readlane_b32 s79, v254, 10
	s_waitcnt vmcnt(7)
	v_addc_co_u32_e32 v47, vcc, 0, v3, vcc
	v_add_co_u32_e32 v48, vcc, s72, v2
	s_mov_b32 s72, 0x30000
	s_nop 0
	v_addc_co_u32_e32 v49, vcc, 0, v3, vcc
	v_add_co_u32_e32 v50, vcc, s72, v2
	s_mov_b32 s72, 0x32000
	s_nop 0
	v_addc_co_u32_e32 v51, vcc, 0, v3, vcc
	s_waitcnt vmcnt(6)
	v_add_co_u32_e32 v52, vcc, s72, v2
	s_mov_b32 s72, 0x34000
	s_waitcnt vmcnt(5)
	v_addc_co_u32_e32 v53, vcc, 0, v3, vcc
	s_waitcnt vmcnt(4)
	v_add_co_u32_e32 v54, vcc, s72, v2
	s_mov_b32 s72, 0x36000
	s_waitcnt vmcnt(3)
	v_addc_co_u32_e32 v55, vcc, 0, v3, vcc
	s_waitcnt vmcnt(2)
	v_add_co_u32_e32 v56, vcc, s72, v2
	s_mov_b32 s72, 0x38000
	s_waitcnt vmcnt(1)
	v_addc_co_u32_e32 v57, vcc, 0, v3, vcc
	v_add_co_u32_e32 v58, vcc, s72, v2
	s_mov_b32 s72, 0x3a000
	s_nop 0
	v_addc_co_u32_e32 v59, vcc, 0, v3, vcc
	v_add_co_u32_e32 v60, vcc, s72, v2
	s_mov_b32 s72, 0x3e000
	s_nop 0
	v_addc_co_u32_e32 v61, vcc, 0, v3, vcc
	v_add_co_u32_e32 v62, vcc, s33, v2
	v_readlane_b32 s80, v254, 11
	s_nop 0
	v_addc_co_u32_e32 v63, vcc, 0, v3, vcc
	v_add_co_u32_e32 v64, vcc, s72, v2
	s_mov_b32 s72, 0x40000
	s_nop 0
	v_addc_co_u32_e32 v65, vcc, 0, v3, vcc
	v_add_co_u32_e32 v66, vcc, s72, v2
	s_mov_b32 s72, 0x44000
	s_nop 0
	v_addc_co_u32_e32 v67, vcc, 0, v3, vcc
	v_add_co_u32_e32 v68, vcc, s66, v2
	v_readlane_b32 s81, v254, 12
	s_nop 0
	v_addc_co_u32_e32 v69, vcc, 0, v3, vcc
	v_add_co_u32_e32 v70, vcc, s72, v2
	s_mov_b32 s72, 0x46000
	s_nop 0
	v_addc_co_u32_e32 v71, vcc, 0, v3, vcc
	v_add_co_u32_e32 v72, vcc, s72, v2
	s_mov_b32 s72, 0x48000
	s_nop 0
	v_addc_co_u32_e32 v73, vcc, 0, v3, vcc
	v_add_co_u32_e32 v74, vcc, s72, v2
	s_mov_b32 s72, 0x4a000
	s_nop 0
	v_addc_co_u32_e32 v75, vcc, 0, v3, vcc
	v_add_co_u32_e32 v76, vcc, s72, v2
	s_mov_b32 s72, 0x4c000
	s_nop 0
	v_addc_co_u32_e32 v77, vcc, 0, v3, vcc
	v_add_co_u32_e32 v78, vcc, s72, v2
	s_mov_b32 s72, 0x4e000
	s_nop 0
	v_addc_co_u32_e32 v79, vcc, 0, v3, vcc
	v_add_co_u32_e32 v80, vcc, s72, v2
	s_mov_b32 s72, 0x54000
	s_nop 0
	v_addc_co_u32_e32 v81, vcc, 0, v3, vcc
	v_add_co_u32_e32 v82, vcc, s39, v2
	v_readlane_b32 s82, v254, 13
	s_nop 0
	v_addc_co_u32_e32 v83, vcc, 0, v3, vcc
	v_add_co_u32_e32 v84, vcc, s18, v2
	v_readlane_b32 s83, v254, 14
	s_nop 0
	v_addc_co_u32_e32 v85, vcc, 0, v3, vcc
	v_add_co_u32_e32 v86, vcc, s72, v2
	s_mov_b32 s72, 0x56000
	s_nop 0
	v_addc_co_u32_e32 v87, vcc, 0, v3, vcc
	v_add_co_u32_e32 v88, vcc, s72, v2
	s_mov_b32 s72, 0x5a000
	s_nop 0
	v_addc_co_u32_e32 v89, vcc, 0, v3, vcc
	v_add_co_u32_e32 v90, vcc, s40, v2
	v_readlane_b32 s86, v254, 17
	s_nop 0
	v_addc_co_u32_e32 v91, vcc, 0, v3, vcc
; __device__ __forceinline__ unsigned pk2(float lo, float hi) { typedef float f2_t __attribute__((ext_vector_type(2))); typedef __bf16 b2_t __attribute__((ext_vector_type(2))); const f2_t v = {lo, hi}; return __builtin_bit_cast(unsigned, __builtin_convertvector(v, b2_t)); }
; __device__ __forceinline__ void transpose_item(const float* W, int K, int N, bf16* WT, int mode, int row_off, const float* gain, int item, int lane) {
;     ...
;     for (int i = 0; i < 64; ++i) v[i] = src[(size_t)i * N];
;     if (gain) {
; #pragma unroll
;         for (int i = 0; i < 64; ++i) v[i] *= gain[k0 + i];
;     }
;     bf16* dst = WT + (size_t)(rbase + lane) * K + k0;
; #pragma unroll
;     for (int c = 0; c < 8; ++c) { v4u o; o.x = pk2(v[8 * c], v[8 * c + 1]); o.y = pk2(v[8 * c + 2], v[8 * c + 3]); o.z = pk2(v[8 * c + 4], v[8 * c + 5]); o.w = pk2(v[8 * c + 6], v[8 * c + 7]);
;         *(v4u*)(dst + 8 * c) = o; }
	v_add_co_u32_e32 v92, vcc, s72, v2
	s_mov_b32 s72, 0x5c000
	s_nop 0
	v_addc_co_u32_e32 v93, vcc, 0, v3, vcc
	v_add_co_u32_e32 v94, vcc, s72, v2
	s_mov_b32 s72, 0x5e000
	s_nop 0
	v_addc_co_u32_e32 v95, vcc, 0, v3, vcc
	v_add_co_u32_e32 v100, vcc, s72, v2
	s_mov_b32 s72, 0x60000
	s_nop 0
	v_addc_co_u32_e32 v101, vcc, 0, v3, vcc
	v_add_co_u32_e32 v102, vcc, s72, v2
	s_mov_b32 s72, 0x62000
	s_nop 0
	v_addc_co_u32_e32 v103, vcc, 0, v3, vcc
	v_add_co_u32_e32 v104, vcc, s72, v2
	s_mov_b32 s72, 0x64000
	s_nop 0
	v_addc_co_u32_e32 v105, vcc, 0, v3, vcc
	v_add_co_u32_e32 v106, vcc, s72, v2
	s_mov_b32 s72, 0x66000
	s_nop 0
	v_addc_co_u32_e32 v107, vcc, 0, v3, vcc
	v_add_co_u32_e32 v108, vcc, s72, v2
	s_mov_b32 s72, 0x6a000
	s_nop 0
	v_addc_co_u32_e32 v109, vcc, 0, v3, vcc
	v_add_co_u32_e32 v110, vcc, s44, v2
	v_readlane_b32 s87, v254, 18
	s_nop 0
	v_addc_co_u32_e32 v111, vcc, 0, v3, vcc
	v_add_co_u32_e32 v112, vcc, s72, v2
	s_mov_b32 s72, 0x6c000
	s_nop 0
	v_addc_co_u32_e32 v113, vcc, 0, v3, vcc
	v_add_co_u32_e32 v114, vcc, s72, v2
	s_mov_b32 s72, 0x70000
	s_nop 0
	v_addc_co_u32_e32 v115, vcc, 0, v3, vcc
	v_add_co_u32_e32 v116, vcc, s25, v2
	v_readlane_b32 s88, v254, 19
	s_nop 0
	v_addc_co_u32_e32 v117, vcc, 0, v3, vcc
	v_add_co_u32_e32 v118, vcc, s72, v2
	s_mov_b32 s72, 0x72000
	s_nop 0
	v_addc_co_u32_e32 v119, vcc, 0, v3, vcc
	v_add_co_u32_e32 v120, vcc, s72, v2
	s_mov_b32 s72, 0x74000
	s_nop 0
	v_addc_co_u32_e32 v121, vcc, 0, v3, vcc
	v_add_co_u32_e32 v122, vcc, s72, v2
	s_mov_b32 s72, 0x76000
	s_nop 0
	v_addc_co_u32_e32 v123, vcc, 0, v3, vcc
	v_add_co_u32_e32 v124, vcc, s72, v2
	s_mov_b32 s72, 0x78000
	s_nop 0
	v_addc_co_u32_e32 v125, vcc, 0, v3, vcc
	v_add_co_u32_e32 v126, vcc, s72, v2
	s_mov_b32 s72, 0x7a000
	s_nop 0
	v_addc_co_u32_e32 v127, vcc, 0, v3, vcc
	v_add_co_u32_e32 v128, vcc, s72, v2
	s_mov_b32 s72, 0x7c000
	s_nop 0
	v_addc_co_u32_e32 v129, vcc, 0, v3, vcc
	v_add_co_u32_e32 v130, vcc, s72, v2
	v_readlane_b32 s89, v254, 20
	s_nop 0
	v_addc_co_u32_e32 v131, vcc, 0, v3, vcc
	v_add_co_u32_e32 v132, vcc, s75, v2
	v_readlane_b32 s90, v254, 21
	s_nop 0
	v_addc_co_u32_e32 v133, vcc, 0, v3, vcc
	global_load_dword v99, v[4:5], off
	global_load_dword v134, v[6:7], off
	global_load_dword v135, v[8:9], off
	global_load_dword v136, v[10:11], off
	global_load_dword v137, v[12:13], off
	global_load_dword v138, v[14:15], off
	global_load_dword v139, v[16:17], off
	global_load_dword v2, v[18:19], off
	global_load_dword v3, v[20:21], off
	global_load_dword v6, v[22:23], off
	global_load_dword v7, v[24:25], off
	global_load_dword v8, v[26:27], off
	global_load_dword v9, v[28:29], off
	global_load_dword v10, v[30:31], off
	global_load_dword v11, v[32:33], off
	global_load_dword v4, v[34:35], off
	global_load_dword v5, v[36:37], off
	global_load_dword v12, v[38:39], off
	global_load_dword v13, v[40:41], off
	global_load_dword v16, v[42:43], off
	global_load_dword v17, v[44:45], off
	global_load_dword v18, v[46:47], off
	global_load_dword v19, v[48:49], off
	global_load_dword v14, v[50:51], off
	global_load_dword v15, v[52:53], off
	global_load_dword v20, v[54:55], off
	global_load_dword v21, v[56:57], off
	global_load_dword v24, v[58:59], off
	global_load_dword v25, v[60:61], off
	global_load_dword v26, v[62:63], off
	global_load_dword v27, v[64:65], off
	global_load_dword v22, v[66:67], off
	global_load_dword v23, v[68:69], off
	global_load_dword v28, v[70:71], off
	global_load_dword v29, v[72:73], off
	global_load_dword v32, v[74:75], off
	global_load_dword v33, v[76:77], off
	global_load_dword v34, v[78:79], off
	global_load_dword v35, v[80:81], off
	global_load_dword v30, v[82:83], off
	global_load_dword v31, v[84:85], off
	global_load_dword v36, v[86:87], off
	global_load_dword v37, v[88:89], off
	global_load_dword v40, v[90:91], off
	global_load_dword v41, v[92:93], off
	global_load_dword v42, v[94:95], off
	global_load_dword v43, v[100:101], off
	global_load_dword v38, v[102:103], off
	global_load_dword v39, v[104:105], off
	global_load_dword v44, v[106:107], off
	global_load_dword v45, v[108:109], off
	global_load_dword v48, v[110:111], off
	global_load_dword v49, v[112:113], off
	global_load_dword v50, v[114:115], off
	global_load_dword v51, v[116:117], off
	global_load_dword v46, v[118:119], off
	global_load_dword v60, v0, s[0:1]
	global_load_dword v47, v[120:121], off
	global_load_dword v52, v[122:123], off
	global_load_dword v53, v[124:125], off
	global_load_dword v54, v[126:127], off
	global_load_dword v55, v[128:129], off
	global_load_dword v56, v[130:131], off
	global_load_dword v57, v[132:133], off
	v_or_b32_e32 v58, s64, v188
	v_mul_u32_u24_e32 v58, 0x1600, v58
	v_readlane_b32 s0, v255, 8
	v_lshlrev_b32_e32 v58, 1, v58
	v_mov_b32_e32 v59, v1
	v_readlane_b32 s1, v255, 9
	v_readlane_b32 s91, v254, 22
	s_waitcnt vmcnt(61)
	v_cvt_pk_bf16_f32 v61, v134, v135
	v_lshl_add_u64 v[58:59], s[0:1], 0, v[58:59]
	v_lshl_add_u64 v[58:59], v[58:59], 0, s[30:31]
	s_waitcnt vmcnt(59)
	v_cvt_pk_bf16_f32 v62, v136, v137
	s_waitcnt vmcnt(57)
	v_cvt_pk_bf16_f32 v63, v138, v139
	s_waitcnt vmcnt(7)
	v_cvt_pk_bf16_f32 v60, v60, v99
	v_lshrrev_b32_e32 v200, 6, v189
	v_mul_u32_u24_e32 v201, 0x90, v188
	v_mul_u32_u24_e32 v200, 0x2400, v200
	v_add_u32_e32 v200, v200, v201
	ds_write_b128 v200, v[60:63]
	s_nop 1

; __device__ __forceinline__ void transpose_item(const float* W, int K, int N, bf16* WT, int mode, int row_off, const float* gain, int item, int lane) {
;     const int nblk = N / 64, kb = item / nblk, nb = item % nblk, k0 = 64 * kb, n0 = 64 * nb;
;     const int rbase = (mode == 0) ? (row_off + n0) : ((n0 >> 7) * 256 + (n0 & 127) + row_off);
;     const float* src = W + (size_t)k0 * N + n0 + lane;
;     float v[64];
; #pragma unroll
;     for (int i = 0; i < 64; ++i) v[i] = src[(size_t)i * N];
.LBB0_37:
	s_andn2_b64 vcc, exec, s[0:1]
	s_cbranch_vccnz .LBB0_39
	s_add_i32 s0, s62, 0xf500
	s_and_b32 s1, s0, 0xffff
	s_mul_i32 s1, s1, 0xba2f
	s_lshr_b32 s30, s1, 16
	s_lshr_b32 s1, s1, 22
	s_mulk_i32 s1, 0x58
	s_sub_i32 s0, s0, s1
	s_and_b32 s0, s0, 0xffff
	s_lshl_b32 s1, s0, 6
	s_lshl_b32 s64, s0, 7
	s_and_b32 s1, s1, 64
	s_and_b32 s30, s30, 0xffc0
	v_readlane_b32 s76, v254, 7
	s_or_b32 s64, s1, s64
	s_mul_i32 s1, s30, 0x5800
	v_readlane_b32 s82, v254, 13
	v_readlane_b32 s83, v254, 14
	s_add_u32 s1, s82, s1
	s_addc_u32 s72, s83, 0
	s_lshl_b32 s0, s0, 8
	s_add_u32 s0, s1, s0
	s_addc_u32 s1, s72, 0
	v_lshl_add_u64 v[2:3], s[0:1], 0, v[0:1]
	v_add_co_u32_e32 v4, vcc, s29, v2
	s_lshl_b32 s30, s30, 1
	s_nop 0
	v_addc_co_u32_e32 v5, vcc, 0, v3, vcc
	v_add_co_u32_e32 v6, vcc, s67, v2
	v_readlane_b32 s77, v254, 8
	s_nop 0
	v_addc_co_u32_e32 v7, vcc, 0, v3, vcc
	v_add_co_u32_e32 v8, vcc, s15, v2
	v_readlane_b32 s78, v254, 9
	s_nop 0
	v_addc_co_u32_e32 v9, vcc, 0, v3, vcc
	v_add_co_u32_e32 v10, vcc, s17, v2
	v_readlane_b32 s79, v254, 10
	s_nop 0
	v_addc_co_u32_e32 v11, vcc, 0, v3, vcc
	v_add_co_u32_e32 v12, vcc, s45, v2
	v_readlane_b32 s80, v254, 11
	s_nop 0
	v_addc_co_u32_e32 v13, vcc, 0, v3, vcc
	v_add_co_u32_e32 v14, vcc, s46, v2
	v_readlane_b32 s81, v254, 12
	s_nop 0
	v_addc_co_u32_e32 v15, vcc, 0, v3, vcc
	v_add_co_u32_e32 v16, vcc, s63, v2
	v_readlane_b32 s84, v254, 15
	s_nop 0
	v_addc_co_u32_e32 v17, vcc, 0, v3, vcc
	v_add_co_u32_e32 v18, vcc, s22, v2
	v_readlane_b32 s85, v254, 16
	s_nop 0
	v_addc_co_u32_e32 v19, vcc, 0, v3, vcc
	v_add_co_u32_e32 v20, vcc, s65, v2
	v_readlane_b32 s86, v254, 17
	s_nop 0
	v_addc_co_u32_e32 v21, vcc, 0, v3, vcc
	v_add_co_u32_e32 v22, vcc, s4, v2
	v_readlane_b32 s87, v254, 18
	s_nop 0
	v_addc_co_u32_e32 v23, vcc, 0, v3, vcc
	v_add_co_u32_e32 v24, vcc, s33, v2
	v_readlane_b32 s88, v254, 19
	s_nop 0
	v_addc_co_u32_e32 v25, vcc, 0, v3, vcc
	v_add_co_u32_e32 v26, vcc, s66, v2
	v_readlane_b32 s89, v254, 20
	s_nop 0
	v_addc_co_u32_e32 v27, vcc, 0, v3, vcc
	v_add_co_u32_e32 v28, vcc, s5, v2
	v_readlane_b32 s90, v254, 21
	s_nop 0
	v_addc_co_u32_e32 v29, vcc, 0, v3, vcc
	v_add_co_u32_e32 v30, vcc, s69, v2
	v_readlane_b32 s91, v254, 22
	s_nop 0
	v_addc_co_u32_e32 v31, vcc, 0, v3, vcc
	v_add_co_u32_e32 v32, vcc, s18, v2
	s_nop 1
	v_addc_co_u32_e32 v33, vcc, 0, v3, vcc
	v_add_co_u32_e32 v34, vcc, s40, v2
	s_nop 1
	v_addc_co_u32_e32 v35, vcc, 0, v3, vcc
	v_add_co_u32_e32 v36, vcc, s26, v2
	s_nop 1
	v_addc_co_u32_e32 v37, vcc, 0, v3, vcc
	v_add_co_u32_e32 v38, vcc, s27, v2
	s_nop 1
	v_addc_co_u32_e32 v39, vcc, 0, v3, vcc
	v_add_co_u32_e32 v40, vcc, s44, v2
	s_nop 1
	v_addc_co_u32_e32 v41, vcc, 0, v3, vcc
	v_add_co_u32_e32 v42, vcc, s25, v2
	s_nop 1
	v_addc_co_u32_e32 v43, vcc, 0, v3, vcc
	v_add_co_u32_e32 v44, vcc, s71, v2
	s_nop 1
	v_addc_co_u32_e32 v45, vcc, 0, v3, vcc
	v_add_co_u32_e32 v46, vcc, s6, v2
	s_waitcnt vmcnt(7)
	s_nop 0
	v_addc_co_u32_e32 v47, vcc, 0, v3, vcc
	v_add_co_u32_e32 v48, vcc, s75, v2
	s_nop 1
	v_addc_co_u32_e32 v49, vcc, 0, v3, vcc
	v_add_co_u32_e32 v50, vcc, s50, v2
	s_nop 1
	v_addc_co_u32_e32 v51, vcc, 0, v3, vcc
	s_waitcnt vmcnt(6)
	v_add_co_u32_e32 v52, vcc, s7, v2
	s_waitcnt vmcnt(5)
	s_nop 0
	v_addc_co_u32_e32 v53, vcc, 0, v3, vcc
	s_waitcnt vmcnt(4)
	v_add_co_u32_e32 v54, vcc, s68, v2
	s_waitcnt vmcnt(3)
	s_nop 0
	v_addc_co_u32_e32 v55, vcc, 0, v3, vcc
	s_waitcnt vmcnt(2)
	v_add_co_u32_e32 v56, vcc, s53, v2
	s_waitcnt vmcnt(1)
; __device__ __forceinline__ unsigned pk2(float lo, float hi) { typedef float f2_t __attribute__((ext_vector_type(2))); typedef __bf16 b2_t __attribute__((ext_vector_type(2))); const f2_t v = {lo, hi}; return __builtin_bit_cast(unsigned, __builtin_convertvector(v, b2_t)); }
; __device__ __forceinline__ void transpose_item(const float* W, int K, int N, bf16* WT, int mode, int row_off, const float* gain, int item, int lane) {
;     ...
;     for (int i = 0; i < 64; ++i) v[i] = src[(size_t)i * N];
;     if (gain) {
; #pragma unroll
;         for (int i = 0; i < 64; ++i) v[i] *= gain[k0 + i];
;     }
;     bf16* dst = WT + (size_t)(rbase + lane) * K + k0;
; #pragma unroll
;     for (int c = 0; c < 8; ++c) { v4u o; o.x = pk2(v[8 * c], v[8 * c + 1]); o.y = pk2(v[8 * c + 2], v[8 * c + 3]); o.z = pk2(v[8 * c + 4], v[8 * c + 5]); o.w = pk2(v[8 * c + 6], v[8 * c + 7]);
;         *(v4u*)(dst + 8 * c) = o; }
	s_nop 0
	v_addc_co_u32_e32 v57, vcc, 0, v3, vcc
	v_add_co_u32_e32 v58, vcc, s70, v2
	s_nop 1
	v_addc_co_u32_e32 v59, vcc, 0, v3, vcc
	v_add_co_u32_e32 v60, vcc, s92, v2
	s_nop 1
	v_addc_co_u32_e32 v61, vcc, 0, v3, vcc
	v_add_co_u32_e32 v62, vcc, s93, v2
	s_nop 1
	v_addc_co_u32_e32 v63, vcc, 0, v3, vcc
	v_add_co_u32_e32 v64, vcc, s94, v2
	s_nop 1
	v_addc_co_u32_e32 v65, vcc, 0, v3, vcc
	v_add_co_u32_e32 v66, vcc, s56, v2
	s_nop 1
	v_addc_co_u32_e32 v67, vcc, 0, v3, vcc
	v_add_co_u32_e32 v68, vcc, s95, v2
	s_nop 1
	v_addc_co_u32_e32 v69, vcc, 0, v3, vcc
	v_add_co_u32_e32 v70, vcc, s96, v2
	s_nop 1
	v_addc_co_u32_e32 v71, vcc, 0, v3, vcc
	v_add_co_u32_e32 v72, vcc, s57, v2
	s_nop 1
	v_addc_co_u32_e32 v73, vcc, 0, v3, vcc
	v_add_co_u32_e32 v74, vcc, s97, v2
	s_nop 1
	v_addc_co_u32_e32 v75, vcc, 0, v3, vcc
	v_add_co_u32_e32 v76, vcc, s74, v2
	s_nop 1
	v_addc_co_u32_e32 v77, vcc, 0, v3, vcc
	v_add_co_u32_e32 v78, vcc, s51, v2
	s_nop 1
	v_addc_co_u32_e32 v79, vcc, 0, v3, vcc
	v_add_co_u32_e32 v80, vcc, s52, v2
	s_nop 1
	v_addc_co_u32_e32 v81, vcc, 0, v3, vcc
	v_add_co_u32_e32 v82, vcc, s59, v2
	s_nop 1
	v_addc_co_u32_e32 v83, vcc, 0, v3, vcc
	v_add_co_u32_e32 v84, vcc, s54, v2
	s_nop 1
	v_addc_co_u32_e32 v85, vcc, 0, v3, vcc
	v_add_co_u32_e32 v86, vcc, s55, v2
	s_nop 1
	v_addc_co_u32_e32 v87, vcc, 0, v3, vcc
	v_add_co_u32_e32 v88, vcc, s60, v2
	s_nop 1
	v_addc_co_u32_e32 v89, vcc, 0, v3, vcc
	v_add_co_u32_e32 v90, vcc, s58, v2
	s_nop 1
	v_addc_co_u32_e32 v91, vcc, 0, v3, vcc
	v_add_co_u32_e32 v92, vcc, s12, v2
	s_nop 1
	v_addc_co_u32_e32 v93, vcc, 0, v3, vcc
	v_add_co_u32_e32 v94, vcc, s13, v2
	s_nop 1
	v_addc_co_u32_e32 v95, vcc, 0, v3, vcc
	v_add_co_u32_e32 v100, vcc, s14, v2
	s_nop 1
	v_addc_co_u32_e32 v101, vcc, 0, v3, vcc
	v_add_co_u32_e32 v102, vcc, s16, v2
	s_nop 1
	v_addc_co_u32_e32 v103, vcc, 0, v3, vcc
	v_add_co_u32_e32 v104, vcc, s19, v2
	s_nop 1
	v_addc_co_u32_e32 v105, vcc, 0, v3, vcc
	v_add_co_u32_e32 v106, vcc, s20, v2
	s_nop 1
	v_addc_co_u32_e32 v107, vcc, 0, v3, vcc
	v_add_co_u32_e32 v108, vcc, s21, v2
	s_nop 1
	v_addc_co_u32_e32 v109, vcc, 0, v3, vcc
	v_add_co_u32_e32 v110, vcc, s23, v2
	s_nop 1
	v_addc_co_u32_e32 v111, vcc, 0, v3, vcc
	v_add_co_u32_e32 v112, vcc, s34, v2
	s_nop 1
	v_addc_co_u32_e32 v113, vcc, 0, v3, vcc
	v_add_co_u32_e32 v114, vcc, s35, v2
	s_nop 1
	v_addc_co_u32_e32 v115, vcc, 0, v3, vcc
	v_add_co_u32_e32 v116, vcc, s36, v2
	s_nop 1
	v_addc_co_u32_e32 v117, vcc, 0, v3, vcc
	v_add_co_u32_e32 v118, vcc, s37, v2
	s_nop 1
	v_addc_co_u32_e32 v119, vcc, 0, v3, vcc
	v_add_co_u32_e32 v120, vcc, s41, v2
	s_nop 1
	v_addc_co_u32_e32 v121, vcc, 0, v3, vcc
	v_add_co_u32_e32 v122, vcc, s42, v2
	s_nop 1
	v_addc_co_u32_e32 v123, vcc, 0, v3, vcc
	v_add_co_u32_e32 v124, vcc, s43, v2
	s_nop 1
	v_addc_co_u32_e32 v125, vcc, 0, v3, vcc
	v_add_co_u32_e32 v126, vcc, s47, v2
	s_nop 1
	v_addc_co_u32_e32 v127, vcc, 0, v3, vcc
	v_add_co_u32_e32 v128, vcc, s48, v2
	s_nop 1
	v_addc_co_u32_e32 v129, vcc, 0, v3, vcc
	v_add_co_u32_e32 v130, vcc, s49, v2
	s_nop 1
	v_addc_co_u32_e32 v131, vcc, 0, v3, vcc
	v_add_co_u32_e32 v132, vcc, s61, v2
	s_nop 1
	v_addc_co_u32_e32 v133, vcc, 0, v3, vcc
	global_load_dword v99, v[4:5], off offset:2048
	global_load_dword v134, v[6:7], off
	global_load_dword v135, v[8:9], off offset:2048
	global_load_dword v136, v[10:11], off
	global_load_dword v137, v[12:13], off offset:2048
	global_load_dword v138, v[14:15], off
	global_load_dword v139, v[16:17], off offset:2048
	global_load_dword v2, v[18:19], off
	global_load_dword v3, v[20:21], off offset:2048
	global_load_dword v6, v[22:23], off
	global_load_dword v7, v[24:25], off offset:2048
	global_load_dword v8, v[26:27], off
	global_load_dword v9, v[28:29], off offset:2048
	global_load_dword v10, v[30:31], off
	global_load_dword v11, v[32:33], off offset:2048
	global_load_dword v4, v[34:35], off
	global_load_dword v5, v[36:37], off offset:2048
	global_load_dword v12, v[38:39], off
	global_load_dword v13, v[40:41], off offset:2048
	global_load_dword v16, v[42:43], off
	global_load_dword v17, v[44:45], off offset:2048
	global_load_dword v18, v[46:47], off
	global_load_dword v19, v[48:49], off offset:2048
	global_load_dword v14, v[50:51], off
	global_load_dword v15, v[52:53], off offset:2048
	global_load_dword v20, v[54:55], off
	global_load_dword v21, v[56:57], off offset:2048
	global_load_dword v24, v[58:59], off
	global_load_dword v25, v[60:61], off offset:2048
	global_load_dword v26, v[62:63], off
	global_load_dword v27, v[64:65], off offset:2048
	global_load_dword v22, v[66:67], off
	global_load_dword v23, v[68:69], off offset:2048
	global_load_dword v28, v[70:71], off
	global_load_dword v29, v[72:73], off offset:2048
	global_load_dword v32, v[74:75], off
	global_load_dword v33, v[76:77], off offset:2048
	global_load_dword v34, v[78:79], off
	global_load_dword v35, v[80:81], off offset:2048
	global_load_dword v30, v[82:83], off
	global_load_dword v31, v[84:85], off offset:2048
	global_load_dword v36, v[86:87], off
	global_load_dword v37, v[88:89], off offset:2048
	global_load_dword v40, v[90:91], off
	global_load_dword v41, v[92:93], off offset:2048
	global_load_dword v42, v[94:95], off
	global_load_dword v43, v[100:101], off offset:2048
	global_load_dword v38, v[102:103], off
	global_load_dword v39, v[104:105], off offset:2048
	global_load_dword v44, v[106:107], off
	global_load_dword v45, v[108:109], off offset:2048
	global_load_dword v48, v[110:111], off
	global_load_dword v49, v[112:113], off offset:2048
	global_load_dword v50, v[114:115], off
	global_load_dword v51, v[116:117], off offset:2048
	global_load_dword v46, v[118:119], off
	global_load_dword v60, v0, s[0:1]
	global_load_dword v47, v[120:121], off offset:2048
	global_load_dword v52, v[122:123], off
	global_load_dword v53, v[124:125], off offset:2048
	global_load_dword v54, v[126:127], off
	global_load_dword v55, v[128:129], off offset:2048
	global_load_dword v56, v[130:131], off
	global_load_dword v57, v[132:133], off offset:2048
	v_or_b32_e32 v58, s64, v188
	v_readlane_b32 s0, v254, 46
	v_lshl_or_b32 v58, v58, 12, v98
	v_mov_b32_e32 v59, v1
	v_readlane_b32 s1, v254, 47
	s_waitcnt vmcnt(61)
	v_cvt_pk_bf16_f32 v61, v134, v135
	v_lshl_add_u64 v[58:59], s[0:1], 0, v[58:59]
	v_lshl_add_u64 v[58:59], v[58:59], 0, s[30:31]
	s_waitcnt vmcnt(59)
	v_cvt_pk_bf16_f32 v62, v136, v137
	s_waitcnt vmcnt(57)
	v_cvt_pk_bf16_f32 v63, v138, v139
	s_waitcnt vmcnt(7)
	v_cvt_pk_bf16_f32 v60, v60, v99
	v_lshrrev_b32_e32 v200, 6, v189
	v_mul_u32_u24_e32 v201, 0x90, v188
	v_mul_u32_u24_e32 v200, 0x2400, v200
	v_add_u32_e32 v200, v200, v201
	ds_write_b128 v200, v[60:63]
	s_nop 1

; __device__ __forceinline__ void transpose_item(const float* W, int K, int N, bf16* WT, int mode, int row_off, const float* gain, int item, int lane) {
;     const int nblk = N / 64, kb = item / nblk, nb = item % nblk, k0 = 64 * kb, n0 = 64 * nb;
;     const int rbase = (mode == 0) ? (row_off + n0) : ((n0 >> 7) * 256 + (n0 & 127) + row_off);
;     const float* src = W + (size_t)k0 * N + n0 + lane;
;     float v[64];
; #pragma unroll
;     for (int i = 0; i < 64; ++i) v[i] = src[(size_t)i * N];
.LBB0_40:
	s_andn2_b64 vcc, exec, s[0:1]
	s_cbranch_vccnz .LBB0_22
	s_mul_hi_i32 s0, s62, 0x2e8ba2e9
	s_lshr_b32 s1, s0, 31
	s_ashr_i32 s0, s0, 4
	s_add_i32 s64, s0, s1
	s_mul_i32 s1, s64, 0xffffd400
	s_mul_i32 s72, s64, 0xffffea00
	s_lshl_b32 s0, s64, 6
	s_add_i32 s1, s8, s1
	s_add_i32 s72, s2, s72
	v_readlane_b32 s76, v254, 7
	s_and_b32 s30, s1, 0xffffff00
	s_ashr_i32 s1, s0, 31
	s_mul_i32 s73, s64, 0x160000
	s_and_b32 s64, s72, 64
	v_readlane_b32 s80, v254, 11
	v_readlane_b32 s81, v254, 12
	s_add_u32 vcc_lo, s80, s73
	s_mul_hi_i32 s73, s0, 0x5800
	s_addc_u32 vcc_hi, s81, s73
	s_ashr_i32 s73, s72, 31
	s_lshl_b64 s[72:73], s[72:73], 2
	s_add_u32 s72, vcc_lo, s72
	s_addc_u32 s73, vcc_hi, s73
	v_lshl_add_u64 v[14:15], s[72:73], 0, v[0:1]
	v_add_co_u32_e32 v2, vcc, s29, v14
	s_or_b32 s30, s30, s64
	s_nop 0
	v_addc_co_u32_e32 v3, vcc, 0, v15, vcc
	v_add_co_u32_e32 v6, vcc, s67, v14
	v_readlane_b32 s77, v254, 8
	s_nop 0
	v_addc_co_u32_e32 v7, vcc, 0, v15, vcc
	v_add_co_u32_e32 v8, vcc, s15, v14
	v_readlane_b32 s78, v254, 9
	s_nop 0
	v_addc_co_u32_e32 v9, vcc, 0, v15, vcc
	v_add_co_u32_e32 v10, vcc, s17, v14
	v_readlane_b32 s79, v254, 10
	s_nop 0
	v_addc_co_u32_e32 v11, vcc, 0, v15, vcc
	v_add_co_u32_e32 v58, vcc, s45, v14
	v_readlane_b32 s82, v254, 13
	s_nop 0
	v_addc_co_u32_e32 v59, vcc, 0, v15, vcc
	v_add_co_u32_e32 v60, vcc, s46, v14
	v_readlane_b32 s83, v254, 14
	s_nop 0
	v_addc_co_u32_e32 v61, vcc, 0, v15, vcc
	v_add_co_u32_e32 v64, vcc, s63, v14
	v_readlane_b32 s84, v254, 15
	s_nop 0
	v_addc_co_u32_e32 v65, vcc, 0, v15, vcc
	v_add_co_u32_e32 v62, vcc, s22, v14
	v_readlane_b32 s85, v254, 16
	s_nop 0
	v_addc_co_u32_e32 v63, vcc, 0, v15, vcc
	v_add_co_u32_e32 v66, vcc, s65, v14
	v_readlane_b32 s86, v254, 17
	s_nop 0
	v_addc_co_u32_e32 v67, vcc, 0, v15, vcc
	v_add_co_u32_e32 v68, vcc, s4, v14
	v_readlane_b32 s87, v254, 18
	s_nop 0
	v_addc_co_u32_e32 v69, vcc, 0, v15, vcc
	v_add_co_u32_e32 v70, vcc, s33, v14
	v_readlane_b32 s88, v254, 19
	s_nop 0
	v_addc_co_u32_e32 v71, vcc, 0, v15, vcc
	v_add_co_u32_e32 v72, vcc, s66, v14
	v_readlane_b32 s89, v254, 20
	s_nop 0
	v_addc_co_u32_e32 v73, vcc, 0, v15, vcc
	v_add_co_u32_e32 v74, vcc, s5, v14
	v_readlane_b32 s90, v254, 21
	s_nop 0
	v_addc_co_u32_e32 v75, vcc, 0, v15, vcc
	v_add_co_u32_e32 v76, vcc, s69, v14
	v_readlane_b32 s91, v254, 22
	s_nop 0
	v_addc_co_u32_e32 v77, vcc, 0, v15, vcc
	v_add_co_u32_e32 v78, vcc, s18, v14
	s_nop 1
	v_addc_co_u32_e32 v79, vcc, 0, v15, vcc
	v_add_co_u32_e32 v80, vcc, s40, v14
	s_nop 1
	v_addc_co_u32_e32 v81, vcc, 0, v15, vcc
	v_add_co_u32_e32 v4, vcc, s26, v14
	s_nop 1
	v_addc_co_u32_e32 v5, vcc, 0, v15, vcc
	v_add_co_u32_e32 v12, vcc, s27, v14
	s_nop 1
	v_addc_co_u32_e32 v13, vcc, 0, v15, vcc
	v_add_co_u32_e32 v16, vcc, s44, v14
	s_nop 1
	v_addc_co_u32_e32 v17, vcc, 0, v15, vcc
	v_add_co_u32_e32 v18, vcc, s25, v14
	s_nop 1
	v_addc_co_u32_e32 v19, vcc, 0, v15, vcc
	v_add_co_u32_e32 v82, vcc, s71, v14
	s_nop 1
	v_addc_co_u32_e32 v83, vcc, 0, v15, vcc
	v_add_co_u32_e32 v84, vcc, s6, v14
	s_nop 1
	v_addc_co_u32_e32 v85, vcc, 0, v15, vcc
	v_add_co_u32_e32 v86, vcc, s75, v14
	s_nop 1
	v_addc_co_u32_e32 v87, vcc, 0, v15, vcc
	v_add_co_u32_e32 v88, vcc, s50, v14
	s_nop 1
	v_addc_co_u32_e32 v89, vcc, 0, v15, vcc
	v_add_co_u32_e32 v20, vcc, s68, v14
	s_nop 1
	v_addc_co_u32_e32 v21, vcc, 0, v15, vcc
	v_add_co_u32_e32 v24, vcc, s53, v14
	s_nop 1
	v_addc_co_u32_e32 v25, vcc, 0, v15, vcc
	v_add_co_u32_e32 v26, vcc, s70, v14
	s_nop 1
	v_addc_co_u32_e32 v27, vcc, 0, v15, vcc
	v_add_co_u32_e32 v90, vcc, s92, v14
	s_nop 1
	v_addc_co_u32_e32 v91, vcc, 0, v15, vcc
	v_add_co_u32_e32 v92, vcc, s93, v14
	s_nop 1
	v_addc_co_u32_e32 v93, vcc, 0, v15, vcc
	v_add_co_u32_e32 v94, vcc, s94, v14
	s_nop 1
	v_addc_co_u32_e32 v95, vcc, 0, v15, vcc
	v_add_co_u32_e32 v22, vcc, s96, v14
	s_nop 1
	v_addc_co_u32_e32 v23, vcc, 0, v15, vcc
	v_add_co_u32_e32 v32, vcc, s57, v14
	s_nop 1
	v_addc_co_u32_e32 v33, vcc, 0, v15, vcc
	v_add_co_u32_e32 v34, vcc, s97, v14
	s_nop 1
	v_addc_co_u32_e32 v35, vcc, 0, v15, vcc
	v_add_co_u32_e32 v100, vcc, s74, v14
	s_nop 1
	v_addc_co_u32_e32 v101, vcc, 0, v15, vcc
	v_add_co_u32_e32 v102, vcc, s51, v14
	s_nop 1
	v_addc_co_u32_e32 v103, vcc, 0, v15, vcc
	v_add_co_u32_e32 v104, vcc, s52, v14
	s_nop 1
	v_addc_co_u32_e32 v105, vcc, 0, v15, vcc
	v_add_co_u32_e32 v28, vcc, s55, v14
	s_nop 1
	v_addc_co_u32_e32 v29, vcc, 0, v15, vcc
	v_add_co_u32_e32 v30, vcc, s60, v14
	s_nop 1
	v_addc_co_u32_e32 v31, vcc, 0, v15, vcc
	v_add_co_u32_e32 v40, vcc, s58, v14
	s_nop 1
	v_addc_co_u32_e32 v41, vcc, 0, v15, vcc
	v_add_co_u32_e32 v42, vcc, s12, v14
	s_nop 1
	v_addc_co_u32_e32 v43, vcc, 0, v15, vcc
	v_add_co_u32_e32 v106, vcc, s13, v14
	s_nop 1
	v_addc_co_u32_e32 v107, vcc, 0, v15, vcc
	v_add_co_u32_e32 v108, vcc, s14, v14
	s_nop 1
	v_addc_co_u32_e32 v109, vcc, 0, v15, vcc
	v_add_co_u32_e32 v36, vcc, s20, v14
	s_nop 1
	v_addc_co_u32_e32 v37, vcc, 0, v15, vcc
	v_add_co_u32_e32 v38, vcc, s21, v14
	s_nop 1
	v_addc_co_u32_e32 v39, vcc, 0, v15, vcc
	v_add_co_u32_e32 v48, vcc, s23, v14
	s_nop 1
	v_addc_co_u32_e32 v49, vcc, 0, v15, vcc
	v_add_co_u32_e32 v50, vcc, s34, v14
	s_nop 1
	v_addc_co_u32_e32 v51, vcc, 0, v15, vcc
	v_add_co_u32_e32 v110, vcc, s35, v14
	s_nop 1
	v_addc_co_u32_e32 v111, vcc, 0, v15, vcc
	v_add_co_u32_e32 v112, vcc, s36, v14
	s_nop 1
	v_addc_co_u32_e32 v113, vcc, 0, v15, vcc
	v_add_co_u32_e32 v114, vcc, s7, v14
	s_nop 1
	v_addc_co_u32_e32 v115, vcc, 0, v15, vcc
	v_add_co_u32_e32 v116, vcc, s56, v14
	s_nop 1
	v_addc_co_u32_e32 v117, vcc, 0, v15, vcc
	v_add_co_u32_e32 v118, vcc, s95, v14
	s_nop 1
	v_addc_co_u32_e32 v119, vcc, 0, v15, vcc
	v_add_co_u32_e32 v120, vcc, s59, v14
	s_nop 1
	v_addc_co_u32_e32 v121, vcc, 0, v15, vcc
	v_add_co_u32_e32 v122, vcc, s54, v14
	s_nop 1
	v_addc_co_u32_e32 v123, vcc, 0, v15, vcc
	v_add_co_u32_e32 v124, vcc, s16, v14
	s_nop 1
	v_addc_co_u32_e32 v125, vcc, 0, v15, vcc
	v_add_co_u32_e32 v126, vcc, s19, v14
	s_nop 1
	v_addc_co_u32_e32 v127, vcc, 0, v15, vcc
	v_add_co_u32_e32 v128, vcc, s37, v14
	s_nop 1
	v_addc_co_u32_e32 v129, vcc, 0, v15, vcc
	v_add_co_u32_e32 v44, vcc, s41, v14
	s_nop 1
	v_addc_co_u32_e32 v45, vcc, 0, v15, vcc
	v_add_co_u32_e32 v46, vcc, s42, v14
	s_waitcnt vmcnt(7)
; __device__ __forceinline__ unsigned pk2(float lo, float hi) { typedef float f2_t __attribute__((ext_vector_type(2))); typedef __bf16 b2_t __attribute__((ext_vector_type(2))); const f2_t v = {lo, hi}; return __builtin_bit_cast(unsigned, __builtin_convertvector(v, b2_t)); }
; __device__ __forceinline__ void transpose_item(const float* W, int K, int N, bf16* WT, int mode, int row_off, const float* gain, int item, int lane) {
;     ...
;     for (int i = 0; i < 64; ++i) v[i] = src[(size_t)i * N];
;     if (gain) {
; #pragma unroll
;         for (int i = 0; i < 64; ++i) v[i] *= gain[k0 + i];
;     }
;     bf16* dst = WT + (size_t)(rbase + lane) * K + k0;
; #pragma unroll
;     for (int c = 0; c < 8; ++c) { v4u o; o.x = pk2(v[8 * c], v[8 * c + 1]); o.y = pk2(v[8 * c + 2], v[8 * c + 3]); o.z = pk2(v[8 * c + 4], v[8 * c + 5]); o.w = pk2(v[8 * c + 6], v[8 * c + 7]);
;         *(v4u*)(dst + 8 * c) = o; }
	s_nop 0
	v_addc_co_u32_e32 v47, vcc, 0, v15, vcc
	s_waitcnt vmcnt(4)
	v_add_co_u32_e32 v54, vcc, s43, v14
	s_waitcnt vmcnt(3)
	s_nop 0
	v_addc_co_u32_e32 v55, vcc, 0, v15, vcc
	s_waitcnt vmcnt(2)
	v_add_co_u32_e32 v56, vcc, s47, v14
	s_waitcnt vmcnt(1)
	s_nop 0
	v_addc_co_u32_e32 v57, vcc, 0, v15, vcc
	v_add_co_u32_e32 v130, vcc, s48, v14
	s_nop 1
	v_addc_co_u32_e32 v131, vcc, 0, v15, vcc
	v_add_co_u32_e32 v132, vcc, s49, v14
	s_nop 1
	v_addc_co_u32_e32 v133, vcc, 0, v15, vcc
	v_add_co_u32_e32 v14, vcc, s61, v14
	s_nop 1
	v_addc_co_u32_e32 v15, vcc, 0, v15, vcc
	global_load_dword v99, v0, s[72:73]
	global_load_dword v52, v[46:47], off
	global_load_dword v53, v[54:55], off offset:2048
	s_nop 0
	global_load_dword v54, v[56:57], off
	global_load_dword v55, v[130:131], off offset:2048
	s_nop 0
	global_load_dword v56, v[132:133], off
	global_load_dword v57, v[14:15], off offset:2048
	global_load_dword v47, v[44:45], off offset:2048
	s_nop 0
	global_load_dword v44, v[36:37], off
	global_load_dword v45, v[38:39], off offset:2048
	s_nop 0
	global_load_dword v48, v[48:49], off
	s_nop 0
	global_load_dword v49, v[50:51], off offset:2048
	s_nop 0
	global_load_dword v50, v[110:111], off
	global_load_dword v51, v[112:113], off offset:2048
	global_load_dword v46, v[128:129], off
	global_load_dword v39, v[126:127], off offset:2048
	global_load_dword v36, v[28:29], off
	global_load_dword v37, v[30:31], off offset:2048
	s_nop 0
	global_load_dword v40, v[40:41], off
	s_nop 0
	global_load_dword v41, v[42:43], off offset:2048
	s_nop 0
	global_load_dword v42, v[106:107], off
	global_load_dword v43, v[108:109], off offset:2048
	global_load_dword v38, v[124:125], off
	global_load_dword v31, v[122:123], off offset:2048
	global_load_dword v28, v[22:23], off
	global_load_dword v29, v[32:33], off offset:2048
	s_nop 0
	global_load_dword v32, v[34:35], off
	global_load_dword v33, v[100:101], off offset:2048
	s_nop 0
	global_load_dword v34, v[102:103], off
	global_load_dword v35, v[104:105], off offset:2048
	global_load_dword v30, v[120:121], off
	global_load_dword v23, v[118:119], off offset:2048
	s_nop 0
	global_load_dword v20, v[20:21], off
	s_nop 0
	global_load_dword v21, v[24:25], off offset:2048
	s_nop 0
	global_load_dword v24, v[26:27], off
	global_load_dword v25, v[90:91], off offset:2048
	s_nop 0
	global_load_dword v26, v[92:93], off
	global_load_dword v27, v[94:95], off offset:2048
	global_load_dword v22, v[116:117], off
	global_load_dword v15, v[114:115], off offset:2048
	s_nop 0
	global_load_dword v12, v[12:13], off
	s_nop 0
	global_load_dword v13, v[16:17], off offset:2048
	s_nop 0
	global_load_dword v16, v[18:19], off
	global_load_dword v17, v[82:83], off offset:2048
	s_nop 0
	global_load_dword v18, v[84:85], off
	global_load_dword v19, v[86:87], off offset:2048
	global_load_dword v14, v[88:89], off
	s_nop 0
	global_load_dword v5, v[4:5], off offset:2048
	s_nop 0
	global_load_dword v82, v[2:3], off offset:2048
	global_load_dword v83, v[6:7], off
	global_load_dword v84, v[8:9], off offset:2048
	global_load_dword v85, v[10:11], off
	s_nop 0
	global_load_dword v58, v[58:59], off offset:2048
	s_nop 0
	global_load_dword v86, v[60:61], off
	s_nop 0
	global_load_dword v64, v[64:65], off offset:2048
	s_nop 0
	global_load_dword v6, v[68:69], off
	global_load_dword v7, v[70:71], off offset:2048
	global_load_dword v8, v[72:73], off
	global_load_dword v9, v[74:75], off offset:2048
	global_load_dword v10, v[76:77], off
	global_load_dword v11, v[78:79], off offset:2048
	global_load_dword v4, v[80:81], off
	global_load_dword v3, v[66:67], off offset:2048
	global_load_dword v2, v[62:63], off
	v_readlane_b32 s72, v254, 46
	v_readlane_b32 s73, v254, 47
	s_waitcnt vmcnt(15)
	v_cvt_pk_bf16_f32 v60, v99, v82
	s_waitcnt vmcnt(13)
	v_cvt_pk_bf16_f32 v61, v83, v84
	s_waitcnt vmcnt(11)
	v_cvt_pk_bf16_f32 v62, v85, v58
	v_or_b32_e32 v58, s30, v188
	v_ashrrev_i32_e32 v59, 31, v58
	v_lshlrev_b64 v[58:59], 12, v[58:59]
	v_lshl_add_u64 v[58:59], s[72:73], 0, v[58:59]
	v_lshl_add_u64 v[58:59], s[0:1], 1, v[58:59]
	s_waitcnt vmcnt(9)
	v_cvt_pk_bf16_f32 v63, v86, v64
	v_lshrrev_b32_e32 v200, 6, v189
	v_mul_u32_u24_e32 v201, 0x90, v188
	v_mul_u32_u24_e32 v200, 0x2400, v200
	v_add_u32_e32 v200, v200, v201
	ds_write_b128 v200, v[60:63]
	s_nop 1
	s_branch .LBB0_22
